# LN1 row loop: post_g/post_b loaded once per wave, the 8 modulation vectors of a row issued at the loop head ahead of the next-row prefetch, counted waits instead of eight load->wait rounds per row
# speedup vs baseline: 1.0075x; 1.0075x over previous
.LBB0_689:
	s_or_b64 exec, exec, s[6:7]
	s_load_dword s3, s[0:1], 0x108
	v_cmp_lt_i32_e32 vcc, 6, v10
	s_waitcnt lgkmcnt(0)
	s_cmp_lt_i32 s3, 8
	s_cselect_b64 s[6:7], -1, 0
	s_and_b64 s[6:7], s[6:7], vcc
	s_and_saveexec_b64 s[16:17], s[6:7]
	s_cbranch_execz .LBB0_751
	s_load_dword s3, s[0:1], 0x640
	v_lshl_add_u32 v28, s2, 2, v206
	s_add_u32 s18, s0, 0x640
	s_movk_i32 s38, 0x4000
	s_addc_u32 s19, s1, 0
	v_cmp_gt_i32_e32 vcc, s38, v28
	s_and_saveexec_b64 s[20:21], vcc
	s_cbranch_execz .LBB0_696
	s_load_dwordx4 s[8:11], s[0:1], 0xf8
	v_ashrrev_i32_e32 v29, 31, v28
	v_lshlrev_b32_e32 v0, 2, v176
	v_lshlrev_b64 v[2:3], 11, v[28:29]
	v_and_b32_e32 v16, 0xfc, v0
	v_mov_b32_e32 v1, 0
	v_lshlrev_b32_e32 v0, 1, v16
	s_waitcnt lgkmcnt(0)
	v_lshl_add_u64 v[2:3], s[10:11], 0, v[2:3]
	v_lshl_add_u64 v[4:5], v[2:3], 0, v[0:1]
	s_mov_b64 s[6:7], 0x6200000
	v_lshl_add_u64 v[6:7], v[4:5], 0, s[6:7]
	s_mov_b32 s6, 0x6200000
	v_add_co_u32_e32 v4, vcc, s6, v4
	s_load_dwordx4 s[12:15], s[0:1], 0x48
	s_nop 0
	v_addc_co_u32_e32 v5, vcc, 0, v5, vcc
	global_load_dwordx2 v[30:31], v[6:7], off offset:1536
	global_load_dwordx2 v[32:33], v[6:7], off offset:1024
	global_load_dwordx2 v[34:35], v[6:7], off offset:512
	global_load_dwordx2 v[36:37], v[4:5], off
	v_mbcnt_lo_u32_b32 v0, -1, 0
	v_mbcnt_hi_u32_b32 v17, -1, v0
	v_and_b32_e32 v6, 64, v17
	s_lshl_b32 s26, s3, 2
	v_xor_b32_e32 v18, 16, v17
	v_add_u32_e32 v21, 64, v6
	v_add_u32_e32 v14, s26, v28
	v_xor_b32_e32 v19, 32, v17
	v_or_b32_e32 v0, 0x100, v16
	v_cmp_lt_i32_e32 vcc, v18, v21
	v_and_b32_e32 v20, 63, v176
	v_lshlrev_b64 v[12:13], 12, v[28:29]
	v_ashrrev_i32_e32 v15, 31, v14
	v_lshlrev_b32_e32 v6, 2, v0
	v_cndmask_b32_e32 v0, v17, v18, vcc
	v_cmp_lt_i32_e32 vcc, v19, v21
	s_ashr_i32 s27, s26, 31
	v_or_b32_e32 v8, 0x200, v16
	v_or_b32_e32 v10, 0x300, v16
	v_lshl_or_b32 v12, v20, 4, v12
	v_lshlrev_b64 v[14:15], 11, v[14:15]
	v_cndmask_b32_e32 v17, v17, v19, vcc
	v_lshlrev_b32_e32 v29, 2, v0
	v_lshlrev_b32_e32 v0, 2, v16
	s_mov_b64 s[28:29], 0
	s_movk_i32 s39, 0x3fff
	v_mov_b32_e32 v38, 0x358637bd
	s_mov_b32 s40, 0x800000
	s_movk_i32 s41, 0xc00
	v_mov_b32_e32 v39, 0x3000
	s_movk_i32 s42, 0x1fff
	v_mov_b32_e32 v40, 0x2400
	s_mov_b64 s[30:31], 0x1000
	s_mov_b32 s43, 0x200000
	v_mov_b32_e32 v5, v1
	v_mov_b32_e32 v7, v1
	v_mov_b32_e32 v9, v1
	v_mov_b32_e32 v11, v1
	s_lshl_b64 s[34:35], s[26:27], 11
	s_lshl_b64 s[36:37], s[26:27], 12
	v_lshlrev_b32_e32 v4, 2, v16
	v_lshlrev_b32_e32 v8, 2, v8
	v_lshlrev_b32_e32 v10, 2, v10
	v_lshlrev_b32_e32 v41, 2, v17
	v_lshl_add_u64 v[12:13], s[8:9], 0, v[12:13]
	v_lshl_add_u64 v[14:15], s[10:11], 0, v[14:15]
	s_waitcnt lgkmcnt(0)
	v_lshl_add_u64 v[16:17], s[12:13], 0, v[0:1]
	v_lshl_add_u64 v[18:19], s[14:15], 0, v[0:1]
	v_lshlrev_b32_e32 v0, 3, v20
	s_waitcnt vmcnt(3)
	v_mov_b64_e32 v[20:21], v[30:31]
	s_waitcnt vmcnt(2)
	v_mov_b64_e32 v[22:23], v[32:33]
	s_waitcnt vmcnt(1)
	v_mov_b64_e32 v[24:25], v[34:35]
	s_waitcnt vmcnt(0)
	v_mov_b64_e32 v[26:27], v[36:37]
	global_load_dwordx4 v[84:87], v[16:17], off
	global_load_dwordx4 v[88:91], v[18:19], off
	global_load_dwordx4 v[92:95], v[16:17], off offset:1024
	global_load_dwordx4 v[96:99], v[18:19], off offset:1024
	global_load_dwordx4 v[100:103], v[16:17], off offset:2048
	global_load_dwordx4 v[104:107], v[18:19], off offset:2048
	global_load_dwordx4 v[108:111], v[16:17], off offset:3072
	global_load_dwordx4 v[112:115], v[18:19], off offset:3072
	s_waitcnt vmcnt(0)
	s_branch .LBB0_693
.LBB0_692:
	s_or_b64 exec, exec, s[8:9]
	v_lshlrev_b32_e32 v44, 16, v36
	v_and_b32_e32 v45, 0xffff0000, v36
	v_lshlrev_b32_e32 v48, 16, v34
	v_and_b32_e32 v49, 0xffff0000, v34
	v_lshlrev_b32_e32 v46, 16, v37
	v_lshlrev_b32_e32 v50, 16, v35
	v_lshlrev_b32_e32 v52, 16, v32
	v_and_b32_e32 v53, 0xffff0000, v32
	v_lshlrev_b32_e32 v54, 16, v33
	v_and_b32_e32 v55, 0xffff0000, v33
	v_lshlrev_b32_e32 v56, 16, v30
	v_and_b32_e32 v57, 0xffff0000, v30
	v_lshlrev_b32_e32 v58, 16, v31
	v_and_b32_e32 v59, 0xffff0000, v31
	v_mov_b32_e32 v30, v48
	v_mov_b32_e32 v31, v44
	v_mov_b32_e32 v32, v49
	v_mov_b32_e32 v33, v45
	v_and_b32_e32 v47, 0xffff0000, v37
	v_and_b32_e32 v51, 0xffff0000, v35
	v_pk_add_f32 v[30:31], v[30:31], v[32:33]
	v_mov_b32_e32 v32, v50
	v_mov_b32_e32 v33, v46
	v_pk_add_f32 v[30:31], v[30:31], v[32:33]
	v_mov_b32_e32 v32, v51
	v_mov_b32_e32 v33, v47
	v_pk_add_f32 v[30:31], v[30:31], v[32:33]
	v_mov_b32_e32 v32, v57
	v_add_f32_e32 v31, 0, v31
	v_add_f32_e32 v34, v30, v31
	v_mov_b32_e32 v30, v56
	v_mov_b32_e32 v31, v52
	v_mov_b32_e32 v33, v53
	v_pk_add_f32 v[30:31], v[30:31], v[32:33]
	v_mov_b32_e32 v32, v58
	v_mov_b32_e32 v33, v54
	v_pk_add_f32 v[30:31], v[30:31], v[32:33]
	v_mov_b32_e32 v32, v59
	v_mov_b32_e32 v33, v55
	v_pk_add_f32 v[30:31], v[30:31], v[32:33]
	s_and_b64 s[6:7], exec, s[6:7]
	v_add_f32_e32 v31, v31, v34
	v_add_f32_e32 v43, v30, v31
	s_nop 1
	v_add_f32_dpp v43, v43, v43 quad_perm:[1,0,3,2] row_mask:0xf bank_mask:0xf bound_ctrl:1
	v_lshl_add_u64 v[14:15], v[14:15], 0, s[34:35]
	s_or_b64 s[28:29], s[6:7], s[28:29]
	v_add_f32_dpp v43, v43, v43 quad_perm:[2,3,0,1] row_mask:0xf bank_mask:0xf bound_ctrl:1
	s_nop 1
	v_add_f32_dpp v43, v43, v43 row_half_mirror row_mask:0xf bank_mask:0xf bound_ctrl:1
	s_nop 1
	v_add_f32_dpp v43, v43, v43 row_mirror row_mask:0xf bank_mask:0xf bound_ctrl:1
	ds_bpermute_b32 v60, v29, v43
	s_waitcnt lgkmcnt(0)
	v_add_f32_e32 v43, v43, v60
	ds_bpermute_b32 v60, v41, v43
	s_waitcnt lgkmcnt(0)
	v_add_f32_e32 v43, v43, v60
	v_mul_f32_e32 v60, 0x3a800000, v43
	v_pk_add_f32 v[44:45], v[44:45], v[60:61] op_sel_hi:[1,0] neg_lo:[0,1] neg_hi:[0,1]
	v_pk_add_f32 v[48:49], v[48:49], v[60:61] op_sel_hi:[1,0] neg_lo:[0,1] neg_hi:[0,1]
	v_mov_b32_e32 v64, v45
	v_mov_b32_e32 v65, v49
	v_pk_add_f32 v[46:47], v[46:47], v[60:61] op_sel_hi:[1,0] neg_lo:[0,1] neg_hi:[0,1]
	v_pk_add_f32 v[50:51], v[50:51], v[60:61] op_sel_hi:[1,0] neg_lo:[0,1] neg_hi:[0,1]
	v_mov_b32_e32 v62, v44
	v_mov_b32_e32 v63, v48
	v_pk_mul_f32 v[64:65], v[64:65], v[64:65]
	v_pk_add_f32 v[52:53], v[52:53], v[60:61] op_sel_hi:[1,0] neg_lo:[0,1] neg_hi:[0,1]
	v_pk_fma_f32 v[62:63], v[62:63], v[62:63], v[64:65]
	v_mov_b32_e32 v64, v46
	v_mov_b32_e32 v65, v50
	v_pk_add_f32 v[56:57], v[56:57], v[60:61] op_sel_hi:[1,0] neg_lo:[0,1] neg_hi:[0,1]
	v_pk_fma_f32 v[62:63], v[64:65], v[64:65], v[62:63]
	v_mov_b32_e32 v64, v57
	v_mov_b32_e32 v65, v53
	v_pk_add_f32 v[54:55], v[54:55], v[60:61] op_sel_hi:[1,0] neg_lo:[0,1] neg_hi:[0,1]
	v_pk_add_f32 v[58:59], v[58:59], v[60:61] op_sel_hi:[1,0] neg_lo:[0,1] neg_hi:[0,1]
	v_mov_b32_e32 v60, v56
	v_mov_b32_e32 v61, v52
	v_pk_mul_f32 v[64:65], v[64:65], v[64:65]
	v_mov_b32_e32 v66, v47
	v_mov_b32_e32 v67, v51
	v_pk_fma_f32 v[60:61], v[60:61], v[60:61], v[64:65]
	v_mov_b32_e32 v64, v58
	v_mov_b32_e32 v65, v54
	v_pk_fma_f32 v[62:63], v[66:67], v[66:67], v[62:63]
	v_mov_b32_e32 v66, v59
	v_mov_b32_e32 v67, v55
	v_pk_fma_f32 v[60:61], v[64:65], v[64:65], v[60:61]
	v_add_f32_e32 v43, v62, v63
	v_pk_fma_f32 v[60:61], v[66:67], v[66:67], v[60:61]
	s_nop 0
	v_add_f32_e32 v43, v61, v43
	v_add_f32_e32 v43, v60, v43
	s_nop 1
	v_add_f32_dpp v43, v43, v43 quad_perm:[1,0,3,2] row_mask:0xf bank_mask:0xf bound_ctrl:1
	s_nop 1
	v_add_f32_dpp v43, v43, v43 quad_perm:[2,3,0,1] row_mask:0xf bank_mask:0xf bound_ctrl:1
	s_nop 1
	v_add_f32_dpp v43, v43, v43 row_half_mirror row_mask:0xf bank_mask:0xf bound_ctrl:1
	s_nop 1
	v_add_f32_dpp v43, v43, v43 row_mirror row_mask:0xf bank_mask:0xf bound_ctrl:1
	ds_bpermute_b32 v60, v29, v43
	s_waitcnt lgkmcnt(0)
	v_add_f32_e32 v43, v43, v60
	ds_bpermute_b32 v60, v41, v43
	s_waitcnt lgkmcnt(0)
	v_add_f32_e32 v43, v43, v60
	v_fmamk_f32 v43, v43, 0x3a800000, v38
	v_mul_f32_e32 v60, 0x4b800000, v43
	v_cmp_gt_f32_e32 vcc, s40, v43
	s_nop 1
	v_cndmask_b32_e32 v43, v43, v60, vcc
	v_rsq_f32_e32 v43, v43
	s_nop 0
	v_mul_f32_e32 v60, 0x45800000, v43
	v_cndmask_b32_e32 v60, v43, v60, vcc
	v_pk_mul_f32 v[44:45], v[44:45], v[60:61] op_sel_hi:[1,0]
	v_pk_mul_f32 v[48:49], v[48:49], v[60:61] op_sel_hi:[1,0]
	s_cmp_eq_u64 s[60:61], 0
	s_cbranch_scc1 .Lln1_a0
	s_waitcnt vmcnt(12)
	s_branch .Lln1_a1
.Lln1_a0:
	s_waitcnt vmcnt(8)
.Lln1_a1:
	v_pk_fma_f32 v[30:31], v[84:85], v[44:45], v[88:89]
	v_pk_mul_f32 v[34:35], v[46:47], v[60:61] op_sel_hi:[1,0]
	v_pk_mul_f32 v[50:51], v[50:51], v[60:61] op_sel_hi:[1,0]
	v_pk_fma_f32 v[32:33], v[86:87], v[34:35], v[90:91]
	global_store_dwordx4 v[12:13], v[30:33], off
	v_pk_mul_f32 v[52:53], v[52:53], v[60:61] op_sel_hi:[1,0]
	v_pk_mul_f32 v[54:55], v[54:55], v[60:61] op_sel_hi:[1,0]
	v_pk_mul_f32 v[56:57], v[56:57], v[60:61] op_sel_hi:[1,0]
	v_pk_mul_f32 v[58:59], v[58:59], v[60:61] op_sel_hi:[1,0]
	v_mov_b32_e32 v60, v30
	v_mov_b32_e32 v68, v31
	v_mov_b32_e32 v70, v32
	v_mov_b32_e32 v72, v33
	v_pk_fma_f32 v[34:35], v[92:93], v[48:49], v[96:97]
	v_pk_fma_f32 v[36:37], v[94:95], v[50:51], v[98:99]
	global_store_dwordx4 v[12:13], v[34:37], off offset:1024
	v_mov_b32_e32 v61, v34
	v_mov_b32_e32 v69, v35
	v_mov_b32_e32 v71, v36
	v_pk_add_f32 v[60:61], v[60:61], v[68:69]
	v_mov_b32_e32 v73, v37
	v_pk_add_f32 v[60:61], v[70:71], v[60:61]
	v_pk_fma_f32 v[44:45], v[52:53], v[100:101], v[104:105]
	v_pk_fma_f32 v[46:47], v[54:55], v[102:103], v[106:107]
	global_store_dwordx4 v[12:13], v[44:47], off offset:2048
	v_pk_add_f32 v[60:61], v[72:73], v[60:61]
	v_mov_b32_e32 v68, v45
	v_add_f32_e32 v28, 0, v60
	v_add_f32_e32 v28, v28, v61
	v_mov_b32_e32 v60, v44
	v_mov_b32_e32 v70, v46
	v_mov_b32_e32 v72, v47
	v_pk_fma_f32 v[48:49], v[56:57], v[108:109], v[112:113]
	v_pk_fma_f32 v[50:51], v[58:59], v[110:111], v[114:115]
	global_store_dwordx4 v[12:13], v[48:51], off offset:3072
	v_mov_b32_e32 v61, v48
	v_mov_b32_e32 v69, v49
	v_mov_b32_e32 v71, v50
	v_pk_add_f32 v[60:61], v[60:61], v[68:69]
	v_mov_b32_e32 v73, v51
	v_pk_add_f32 v[60:61], v[60:61], v[70:71]
	v_lshl_add_u64 v[12:13], v[12:13], 0, s[36:37]
	v_pk_add_f32 v[60:61], v[60:61], v[72:73]
	s_nop 0
	v_add_f32_e32 v28, v28, v60
	v_add_f32_e32 v28, v28, v61
	s_nop 1
	v_add_f32_dpp v28, v28, v28 quad_perm:[1,0,3,2] row_mask:0xf bank_mask:0xf bound_ctrl:1
	s_nop 1
	v_add_f32_dpp v28, v28, v28 quad_perm:[2,3,0,1] row_mask:0xf bank_mask:0xf bound_ctrl:1
	s_nop 1
	v_add_f32_dpp v28, v28, v28 row_half_mirror row_mask:0xf bank_mask:0xf bound_ctrl:1
	s_nop 1
	v_add_f32_dpp v28, v28, v28 row_mirror row_mask:0xf bank_mask:0xf bound_ctrl:1
	ds_bpermute_b32 v43, v29, v28
	s_waitcnt lgkmcnt(0)
	v_add_f32_e32 v28, v28, v43
	ds_bpermute_b32 v43, v41, v28
	s_waitcnt lgkmcnt(0)
	v_add_f32_e32 v28, v28, v43
	v_mul_f32_e32 v28, 0x3a800000, v28
	v_pk_add_f32 v[30:31], v[30:31], v[28:29] op_sel_hi:[1,0] neg_lo:[0,1] neg_hi:[0,1]
	v_pk_add_f32 v[66:67], v[34:35], v[28:29] op_sel_hi:[1,0] neg_lo:[0,1] neg_hi:[0,1]
	v_pk_add_f32 v[44:45], v[44:45], v[28:29] op_sel_hi:[1,0] neg_lo:[0,1] neg_hi:[0,1]
	v_pk_add_f32 v[68:69], v[50:51], v[28:29] op_sel_hi:[1,0] neg_lo:[0,1] neg_hi:[0,1]
	v_pk_add_f32 v[70:71], v[48:49], v[28:29] op_sel_hi:[1,0] neg_lo:[0,1] neg_hi:[0,1]
	v_mov_b32_e32 v50, v31
	v_mov_b32_e32 v51, v67
	v_pk_add_f32 v[32:33], v[32:33], v[28:29] op_sel_hi:[1,0] neg_lo:[0,1] neg_hi:[0,1]
	v_pk_add_f32 v[60:61], v[36:37], v[28:29] op_sel_hi:[1,0] neg_lo:[0,1] neg_hi:[0,1]
	v_mov_b32_e32 v48, v30
	v_mov_b32_e32 v49, v66
	v_mov_b32_e32 v78, v71
	v_mov_b32_e32 v79, v45
	v_pk_mul_f32 v[50:51], v[50:51], v[50:51]
	v_pk_add_f32 v[46:47], v[46:47], v[28:29] op_sel_hi:[1,0] neg_lo:[0,1] neg_hi:[0,1]
	v_mov_b32_e32 v34, v32
	v_mov_b32_e32 v35, v60
	v_mov_b32_e32 v76, v70
	v_mov_b32_e32 v77, v44
	v_pk_mul_f32 v[78:79], v[78:79], v[78:79]
	v_pk_fma_f32 v[48:49], v[48:49], v[48:49], v[50:51]
	v_mov_b32_e32 v36, v33
	v_mov_b32_e32 v37, v61
	v_mov_b32_e32 v72, v68
	v_mov_b32_e32 v73, v46
	v_pk_fma_f32 v[50:51], v[76:77], v[76:77], v[78:79]
	v_pk_fma_f32 v[34:35], v[34:35], v[34:35], v[48:49]
	v_mov_b32_e32 v74, v69
	v_mov_b32_e32 v75, v47
	v_pk_fma_f32 v[48:49], v[72:73], v[72:73], v[50:51]
	v_pk_fma_f32 v[34:35], v[36:37], v[36:37], v[34:35]
	v_pk_fma_f32 v[36:37], v[74:75], v[74:75], v[48:49]
	v_add_f32_e32 v28, v34, v35
	v_add_f32_e32 v28, v37, v28
	v_add_f32_e32 v28, v36, v28
	s_nop 0
	v_add_f32_dpp v28, v28, v28 quad_perm:[1,0,3,2] row_mask:0xf bank_mask:0xf bound_ctrl:1
	s_nop 1
	v_add_f32_dpp v28, v28, v28 quad_perm:[2,3,0,1] row_mask:0xf bank_mask:0xf bound_ctrl:1
	s_nop 1
	v_add_f32_dpp v28, v28, v28 row_half_mirror row_mask:0xf bank_mask:0xf bound_ctrl:1
	s_nop 1
	v_add_f32_dpp v28, v28, v28 row_mirror row_mask:0xf bank_mask:0xf bound_ctrl:1
	ds_bpermute_b32 v34, v29, v28
	s_waitcnt lgkmcnt(0)
	v_add_f32_e32 v28, v28, v34
	ds_bpermute_b32 v36, v41, v28
	v_lshl_add_u64 v[34:35], v[2:3], 0, v[0:1]
	v_add_co_u32_e64 v72, s[8:9], s43, v34
	v_lshl_add_u64 v[2:3], v[2:3], 0, s[34:35]
	s_waitcnt lgkmcnt(0)
	v_add_f32_e32 v28, v28, v36
	v_fmamk_f32 v28, v28, 0x3a800000, v38
	v_mul_f32_e32 v36, 0x4b800000, v28
	v_cmp_gt_f32_e32 vcc, s40, v28
	v_addc_co_u32_e64 v73, s[8:9], 0, v35, s[8:9]
	s_nop 0
	v_cndmask_b32_e32 v28, v28, v36, vcc
	v_rsq_f32_e32 v28, v28
	s_cmp_eq_u64 s[60:61], 0
	s_cbranch_scc1 .Lln1_b0
	s_waitcnt vmcnt(8)
	s_branch .Lln1_b1
.Lln1_b0:
	s_waitcnt vmcnt(4)
.Lln1_b1:
	v_pk_add_f32 v[36:37], v[128:129], 1.0 op_sel_hi:[1,0]
	v_mul_f32_e32 v34, 0x45800000, v28
	v_cndmask_b32_e32 v28, v28, v34, vcc
	v_pk_mul_f32 v[30:31], v[30:31], v[28:29] op_sel_hi:[1,0]
	v_pk_mul_f32 v[32:33], v[32:33], v[28:29] op_sel_hi:[1,0]
	v_pk_add_f32 v[34:35], v[126:127], 1.0 op_sel_hi:[1,0]
	v_pk_fma_f32 v[32:33], v[36:37], v[32:33], v[124:125]
	v_pk_fma_f32 v[30:31], v[34:35], v[30:31], v[122:123]
	v_pk_mul_f32 v[50:51], v[66:67], v[28:29] op_sel_hi:[1,0]
	v_cvt_pk_bf16_f32 v30, v30, v31
	v_cvt_pk_bf16_f32 v31, v32, v33
	global_store_dwordx2 v[72:73], v[30:31], off
	v_pk_mul_f32 v[52:53], v[60:61], v[28:29] op_sel_hi:[1,0]
	v_pk_mul_f32 v[44:45], v[44:45], v[28:29] op_sel_hi:[1,0]
	v_pk_mul_f32 v[46:47], v[46:47], v[28:29] op_sel_hi:[1,0]
	v_pk_mul_f32 v[54:55], v[68:69], v[28:29] op_sel_hi:[1,0]
	v_pk_add_f32 v[30:31], v[130:131], 1.0 op_sel_hi:[1,0]
	v_pk_add_f32 v[32:33], v[132:133], 1.0 op_sel_hi:[1,0]
	v_pk_fma_f32 v[30:31], v[30:31], v[50:51], v[134:135]
	v_pk_fma_f32 v[32:33], v[32:33], v[52:53], v[136:137]
	v_cvt_pk_bf16_f32 v30, v30, v31
	v_cvt_pk_bf16_f32 v31, v32, v33
	global_store_dwordx2 v[72:73], v[30:31], off offset:512
	v_pk_add_f32 v[30:31], v[138:139], 1.0 op_sel_hi:[1,0]
	v_pk_add_f32 v[32:33], v[140:141], 1.0 op_sel_hi:[1,0]
	v_pk_fma_f32 v[30:31], v[44:45], v[30:31], v[142:143]
	v_pk_fma_f32 v[32:33], v[46:47], v[32:33], v[144:145]
	v_cvt_pk_bf16_f32 v30, v30, v31
	v_cvt_pk_bf16_f32 v31, v32, v33
	global_store_dwordx2 v[72:73], v[30:31], off offset:1024
	v_pk_mul_f32 v[52:53], v[70:71], v[28:29] op_sel_hi:[1,0]
	s_waitcnt vmcnt(7)
	v_mov_b64_e32 v[30:31], v[20:21]
	v_mov_b64_e32 v[32:33], v[22:23]
	v_mov_b64_e32 v[34:35], v[24:25]
	v_mov_b64_e32 v[36:37], v[26:27]
	v_mov_b32_e32 v28, v42
	v_pk_add_f32 v[44:45], v[146:147], 1.0 op_sel_hi:[1,0]
	v_pk_add_f32 v[46:47], v[148:149], 1.0 op_sel_hi:[1,0]
	v_pk_fma_f32 v[44:45], v[52:53], v[44:45], v[150:151]
	v_pk_fma_f32 v[46:47], v[54:55], v[46:47], v[152:153]
	v_cvt_pk_bf16_f32 v44, v44, v45
	v_cvt_pk_bf16_f32 v45, v46, v47
	global_store_dwordx2 v[72:73], v[44:45], off offset:1536
	s_andn2_b64 exec, exec, s[28:29]
	s_cbranch_execz .LBB0_695
.LBB0_693:
	v_add_u32_e32 v42, s26, v28
	v_add_u32_e32 v43, 0xffffe000, v28
	v_lshrrev_b32_e32 v43, 12, v43
	v_cmp_lt_i32_e32 vcc, s42, v28
	v_mad_u32_u24 v43, v43, s41, v39
	s_nop 1
	v_cndmask_b32_e32 v62, v40, v43, vcc
	v_ashrrev_i32_e32 v63, 31, v62
	v_lshl_add_u64 v[62:63], v[62:63], 2, s[10:11]
	v_lshl_add_u64 v[64:65], v[62:63], 0, s[30:31]
	v_lshl_add_u64 v[62:63], v[62:63], 0, v[4:5]
	v_lshl_add_u64 v[66:67], v[64:65], 0, v[4:5]
	v_lshl_add_u64 v[116:117], v[64:65], 0, v[6:7]
	v_lshl_add_u64 v[118:119], v[64:65], 0, v[8:9]
	v_lshl_add_u64 v[120:121], v[64:65], 0, v[10:11]
	global_load_dwordx4 v[122:125], v[62:63], off
	global_load_dwordx4 v[126:129], v[66:67], off
	global_load_dwordx4 v[130:133], v[116:117], off
	global_load_dwordx4 v[134:137], v[62:63], off offset:1024
	global_load_dwordx4 v[138:141], v[118:119], off
	global_load_dwordx4 v[142:145], v[62:63], off offset:2048
	global_load_dwordx4 v[146:149], v[120:121], off
	global_load_dwordx4 v[150:153], v[62:63], off offset:3072
	v_cmp_gt_i32_e32 vcc, s38, v42
	s_mov_b64 s[60:61], vcc
	v_cmp_lt_i32_e64 s[6:7], s39, v42
	s_and_saveexec_b64 s[8:9], vcc
	s_cbranch_execz .LBB0_692
	v_lshl_add_u64 v[20:21], v[14:15], 0, v[0:1]
	v_add_co_u32_e32 v44, vcc, 0x6200000, v20
	s_nop 1
	v_addc_co_u32_e32 v45, vcc, 0, v21, vcc
	global_load_dwordx2 v[26:27], v[44:45], off
	global_load_dwordx2 v[24:25], v[44:45], off offset:512
	global_load_dwordx2 v[22:23], v[44:45], off offset:1024
	global_load_dwordx2 v[20:21], v[44:45], off offset:1536
	s_branch .LBB0_692
